# phase 0: hand-written software-pipelined weight conversion loop (scalar item decode, next item's loads in flight during the LDS transpose, two register / LDS tile sets)
# speedup vs baseline: 1.0069x; 1.0069x over previous
.LBB0_464:
	v_readlane_b32 s0, v217, 9
	v_readlane_b32 s1, v217, 10
	v_mov_b32_e32 v2, v142
	s_andn2_b64 vcc, exec, s[0:1]
	s_cbranch_vccnz .LBB0_551
	s_waitcnt lgkmcnt(0)
	v_ashrrev_i32_e32 v21, 8, v2
	v_lshlrev_b32_e32 v0, 6, v21
	v_and_b32_e32 v69, 64, v0
	v_and_b32_e32 v0, 15, v2
	v_cvt_f32_ubyte0_e32 v3, v0
	v_ashrrev_i32_e32 v18, 4, v2
	s_movk_i32 s0, 0x400
	v_mul_f32_e32 v3, 0xbf549a78, v3
	v_cmp_gt_i32_e64 s[38:39], s0, v18
	s_movk_i32 s0, 0x300
	v_lshlrev_b32_e32 v6, 4, v2
	v_exp_f32_e32 v5, v3
	v_mul_lo_u32 v3, v18, s0
	v_and_b32_e32 v6, 0xf0, v6
	v_add3_u32 v70, 0, v3, v6
	v_cvt_f32_i32_e32 v3, v18
	v_readlane_b32 s0, v217, 13
	v_readlane_b32 s1, v217, 14
	v_lshlrev_b32_e32 v16, 3, v2
	v_mul_f32_e32 v3, v5, v3
	v_mul_f32_e32 v7, 0.15915494, v3
	v_floor_f32_e32 v7, v7
	v_fma_f32 v7, v3, 0.15915494, -v7
	v_add_u32_e32 v3, 0x200, v2
	v_ashrrev_i32_e32 v3, 4, v3
	v_cvt_f32_i32_e32 v8, v3
	v_ashrrev_i32_e32 v3, 31, v2
	v_cmp_gt_i32_e64 s[40:41], s57, v2
	v_ashrrev_i32_e32 v20, 6, v2
	v_and_b32_e32 v71, 63, v2
	v_lshl_add_u64 v[22:23], v[2:3], 2, s[0:1]
	v_max_i32_e32 v2, 0x3e0, v18
	v_sub_u32_e32 v2, v2, v18
	v_mul_f32_e32 v5, v5, v8
	v_add_u32_e32 v2, 31, v2
	v_cos_f32_e32 v72, v7
	v_sin_f32_e32 v73, v7
	v_mul_f32_e32 v7, 0.15915494, v5
	s_mov_b64 s[0:1], 0x1000
	v_lshrrev_b32_e32 v3, 5, v2
	v_floor_f32_e32 v7, v7
	v_lshl_add_u64 v[24:25], v[22:23], 0, s[0:1]
	s_mov_b64 s[0:1], 0x1800
	v_add_u32_e32 v3, 1, v3
	v_fma_f32 v5, v5, 0.15915494, -v7
	v_lshl_add_u64 v[26:27], v[22:23], 0, s[0:1]
	v_and_b32_e32 v7, 7, v3
	v_and_b32_e32 v3, 0xe0, v2
	s_movk_i32 s0, 0xe0
	v_cmp_ne_u32_e64 s[42:43], s0, v3
	s_movk_i32 s0, 0xdf
	v_cmp_lt_u32_e64 s[44:45], s0, v2
	v_ashrrev_i32_e32 v19, 31, v18
	v_readlane_b32 s0, v214, 6
	v_lshlrev_b64 v[2:3], 2, v[18:19]
	v_readlane_b32 s1, v214, 7
	v_cos_f32_e32 v74, v5
	v_sin_f32_e32 v75, v5
	v_lshl_add_u64 v[28:29], s[0:1], 0, v[2:3]
	v_readlane_b32 s0, v215, 54
	v_readlane_b32 s1, v215, 55
	v_readlane_b32 s10, v214, 0
	v_readlane_b32 s11, v214, 1
	v_lshlrev_b32_e32 v0, 4, v0
	v_and_b32_e32 v4, 0x3f8, v16
	v_lshl_add_u64 v[30:31], s[10:11], 0, v[2:3]
	v_mad_i64_i32 v[2:3], s[0:1], v18, s55, 0
	v_lshl_add_u32 v6, v71, 2, 0
	v_lshlrev_b32_e32 v5, 8, v20
	v_readlane_b32 s12, v214, 2
	v_readlane_b32 s13, v214, 3
	v_readlane_b32 s14, v214, 4
	v_or_b32_e32 v2, v2, v0
	v_add_u32_e32 v68, 0xffff8d80, v21
	v_ashrrev_i32_e32 v17, 31, v16
	v_lshl_add_u64 v[32:33], s[12:13], 0, v[2:3]
	v_sub_u32_e32 v19, 0, v7
	v_lshl_add_u64 v[34:35], s[12:13], 0, v[0:1]
	v_lshlrev_b32_e32 v36, 1, v4
	v_add_u32_e32 v76, v6, v5
	v_readlane_b32 s14, v217, 0
	v_readlane_b32 s2, v215, 56
	v_readlane_b32 s3, v215, 57
	v_readlane_b32 s4, v215, 58
	v_readlane_b32 s5, v215, 59
	v_readlane_b32 s6, v215, 60
	v_readlane_b32 s7, v215, 61
	v_readlane_b32 s8, v215, 62
	v_readlane_b32 s9, v215, 63
	v_readlane_b32 s15, v214, 5
	v_writelane_b32 v249, s0, 0
	v_writelane_b32 v249, s1, 1
	v_writelane_b32 v249, s2, 2
	v_writelane_b32 v249, s3, 3
	v_writelane_b32 v249, s4, 4
	v_writelane_b32 v249, s5, 5
	v_writelane_b32 v249, s6, 6
	v_writelane_b32 v249, s7, 7
	v_writelane_b32 v249, s8, 8
	v_writelane_b32 v249, s9, 9
	v_writelane_b32 v249, s10, 10
	v_writelane_b32 v249, s11, 11
	v_writelane_b32 v249, s12, 12
	v_writelane_b32 v249, s13, 13
	v_writelane_b32 v249, s14, 14
	v_writelane_b32 v249, s15, 15
	v_writelane_b32 v249, s36, 16
	v_writelane_b32 v249, s37, 17
	v_writelane_b32 v249, s38, 18
	v_writelane_b32 v249, s39, 19
	v_writelane_b32 v249, s40, 20
	v_writelane_b32 v249, s41, 21
	v_writelane_b32 v249, s42, 22
	v_writelane_b32 v249, s43, 23
	v_writelane_b32 v249, s44, 24
	v_writelane_b32 v249, s45, 25
	s_waitcnt vmcnt(0) lgkmcnt(0)
	v_readlane_b32 s0, v217, 1
	v_readlane_b32 s1, v217, 2
	s_sub_u32 s0, s0, 0xd0
	s_subb_u32 s1, s1, 0
	v_and_b32_e32 v237, 0xff, v142
	v_lshrrev_b32_e32 v238, 8, v142
	v_mul_u32_u24_e32 v238, 0x4100, v238
	v_lshrrev_b32_e32 v226, 4, v237
	v_and_b32_e32 v227, 15, v237
	v_mul_u32_u24_e32 v229, 260, v226
	v_lshl_add_u32 v229, v227, 4, v229
	v_add_u32_e32 v229, v229, v238
	v_lshrrev_b32_e32 v228, 3, v227
	v_mul_u32_u24_e32 v228, 11264, v228
	v_and_b32_e32 v230, 7, v227
	v_lshl_add_u32 v228, v230, 4, v228
	v_lshlrev_b32_e32 v227, 4, v227
	v_and_b32_e32 v231, 3, v237
	v_lshrrev_b32_e32 v232, 2, v237
	v_mul_u32_u24_e32 v230, 4160, v231
	v_lshl_add_u32 v230, v232, 2, v230
	v_add_u32_e32 v230, v230, v238
	v_lshlrev_b32_e32 v237, 5, v231
	v_lshl_add_u32 v238, v232, 11, v237
	v_and_b32_e32 v233, 15, v232
	v_lshlrev_b32_e32 v233, 6, v233
	v_lshrrev_b32_e32 v237, 1, v231
	v_lshl_add_u32 v233, v237, 10, v233
	v_and_b32_e32 v237, 1, v231
	v_lshl_add_u32 v233, v237, 5, v233
	v_lshrrev_b32_e32 v237, 4, v232
	v_mov_b32_e32 v231, v238
	v_lshl_add_u32 v232, v237, 15, v233
	v_mul_u32_u24_e32 v237, 0x16000, v237
	v_add_u32_e32 v233, v233, v237
	v_readlane_b32 s2, v217, 0
	s_lshl_b32 s2, s2, 1
	v_readfirstlane_b32 s3, v142
	s_lshr_b32 s3, s3, 8
	s_add_u32 s2, s2, s3
	s_mov_b32 s4, 0
	s_mov_b32 s5, s2
	s_cmp_ge_u32 s5, 6784
	s_cselect_b32 s6, 6784, 0
	s_cselect_b32 s7, 1, 0
	s_sub_u32 s5, s5, s6
	s_add_u32 s4, s4, s7
	s_cmp_ge_u32 s5, 6784
	s_cselect_b32 s6, 6784, 0
	s_cselect_b32 s7, 1, 0
	s_sub_u32 s5, s5, s6
	s_add_u32 s4, s4, s7
	s_cmp_ge_u32 s5, 6784
	s_cselect_b32 s6, 6784, 0
	s_cselect_b32 s7, 1, 0
	s_sub_u32 s5, s5, s6
	s_add_u32 s4, s4, s7
	s_cmp_lt_u32 s5, 1408
	s_cbranch_scc1 .Lp0_d1_w0
	s_cmp_lt_u32 s5, 2112
	s_cbranch_scc1 .Lp0_d1_w1
	s_cmp_lt_u32 s5, 3904
	s_cbranch_scc1 .Lp0_d1_w2
	s_cmp_lt_u32 s5, 4160
	s_cbranch_scc1 .Lp0_d1_w3
	s_cmp_lt_u32 s5, 4416
	s_cbranch_scc1 .Lp0_d1_w4
	s_cmp_lt_u32 s5, 4672
	s_cbranch_scc1 .Lp0_d1_w5
	s_cmp_lt_u32 s5, 6080
	s_cbranch_scc1 .Lp0_d1_w6
	s_mov_b32 s6, 6080
	s_mov_b32 s7, 65536
	s_mov_b32 s8, 16
	s_mov_b32 s9, 2816
	s_mov_b32 s10, 4096
	s_mov_b32 s11, 0
	s_mov_b32 s12, 0xa8
	s_mov_b32 s13, 0x2f80000
	s_branch .Lp0_d1_j
.Lp0_d1_w6:
	s_mov_b32 s6, 4672
	s_mov_b32 s7, 11916
	s_mov_b32 s8, 88
	s_mov_b32 s9, 1024
	s_mov_b32 s10, 22528
	s_mov_b32 s11, 1
	s_mov_b32 s12, 0xa0
	s_mov_b32 s13, 0x2480000
	s_branch .Lp0_d1_j
.Lp0_d1_w5:
	s_mov_b32 s6, 4416
	s_mov_b32 s7, 65536
	s_mov_b32 s8, 16
	s_mov_b32 s9, 1024
	s_mov_b32 s10, 4096
	s_mov_b32 s11, 0
	s_mov_b32 s12, 0x98
	s_mov_b32 s13, 0x2280000
	s_branch .Lp0_d1_j
.Lp0_d1_w4:
	s_mov_b32 s6, 4160
	s_mov_b32 s7, 65536
	s_mov_b32 s8, 16
	s_mov_b32 s9, 1024
	s_mov_b32 s10, 4096
	s_mov_b32 s11, 0
	s_mov_b32 s12, 0x90
	s_mov_b32 s13, 0x2080000
	s_branch .Lp0_d1_j
.Lp0_d1_w3:
	s_mov_b32 s6, 3904
	s_mov_b32 s7, 65536
	s_mov_b32 s8, 16
	s_mov_b32 s9, 1024
	s_mov_b32 s10, 4096
	s_mov_b32 s11, 0
	s_mov_b32 s12, 0x88
	s_mov_b32 s13, 0x1e80000
	s_branch .Lp0_d1_j
.Lp0_d1_w2:
	s_mov_b32 s6, 2112
	s_mov_b32 s7, 9363
	s_mov_b32 s8, 112
	s_mov_b32 s9, 1024
	s_mov_b32 s10, 28672
	s_mov_b32 s11, 0
	s_mov_b32 s12, 0x58
	s_mov_b32 s13, 0x1080000
	s_branch .Lp0_d1_j
.Lp0_d1_w1:
	s_mov_b32 s6, 1408
	s_mov_b32 s7, 65536
	s_mov_b32 s8, 16
	s_mov_b32 s9, 2816
	s_mov_b32 s10, 4096
	s_mov_b32 s11, 0
	s_mov_b32 s12, 0x50
	s_mov_b32 s13, 0xb00000
	s_branch .Lp0_d1_j
.Lp0_d1_w0:
	s_mov_b32 s6, 0
	s_mov_b32 s7, 11916
	s_mov_b32 s8, 88
	s_mov_b32 s9, 1024
	s_mov_b32 s10, 22528
	s_mov_b32 s11, 1
	s_mov_b32 s12, 0x48
	s_mov_b32 s13, 0x0
.Lp0_d1_j:
	s_load_dwordx2 s[36:37], s[0:1], s12
	s_sub_u32 s5, s5, s6
	s_mul_i32 s14, s5, s7
	s_lshr_b32 s14, s14, 20
	s_mul_i32 s15, s14, s8
	s_sub_u32 s15, s5, s15
	s_mul_i32 s44, s4, s9
	s_lshl_b32 s45, s14, 6
	s_add_u32 s44, s44, s45
	s_mul_i32 s44, s44, s10
	s_lshr_b32 s45, s15, 1
	s_lshl_b32 s45, s45, 6
	s_and_b32 s6, s15, 1
	s_lshl_b32 s6, s6, 5
	s_add_u32 s45, s45, s6
	s_lshl_b32 s6, s15, 6
	s_cmp_lg_u32 s11, 0
	s_cselect_b32 s45, s45, s6
	s_cselect_b64 vcc, -1, 0
	s_lshl_b32 s45, s45, 2
	s_add_u32 s44, s44, s45
	v_cndmask_b32_e32 v234, v227, v228, vcc
	v_mul_lo_u32 v237, v226, s10
	v_add_u32_e32 v234, v234, v237
	s_mul_hi_u32 s45, s4, 0x3500000
	s_mul_i32 s6, s4, 0x3500000
	s_add_u32 s40, s48, s6
	s_addc_u32 s41, s49, s45
	s_add_u32 s40, s40, 0xf5ce000
	s_addc_u32 s41, s41, 0
	s_add_u32 s40, s40, s13
	s_addc_u32 s41, s41, 0
	s_mul_i32 s45, s15, s9
	s_lshl_b32 s45, s45, 7
	s_cmp_eq_u32 s9, 2816
	s_cselect_b32 s6, 1, 0
	s_or_b32 s6, s6, s11
	s_lshl_b32 s7, s14, 11
	s_lshl_b32 s8, s14, 7
	s_cmp_lg_u32 s6, 0
	s_cselect_b32 s7, s7, s8
	s_cselect_b64 vcc, -1, 0
	s_add_u32 s45, s45, s7
	s_add_u32 s40, s40, s45
	s_addc_u32 s41, s41, 0
	v_cndmask_b32_e32 v237, v231, v232, vcc
	s_cmp_eq_u32 s9, 2816
	s_cselect_b64 vcc, -1, 0
	s_nop 1
	v_cndmask_b32_e32 v235, v237, v233, vcc
	s_lshl_b32 s7, s10, 4
	s_waitcnt lgkmcnt(0)
	s_add_u32 s38, s36, s44
	s_addc_u32 s39, s37, 0
	s_add_u32 s2, s2, 512
	global_load_dwordx4 v[166:169], v234, s[38:39] nt
	s_add_u32 s38, s38, s7
	s_addc_u32 s39, s39, 0
	global_load_dwordx4 v[170:173], v234, s[38:39] nt
	s_add_u32 s38, s38, s7
	s_addc_u32 s39, s39, 0
	global_load_dwordx4 v[174:177], v234, s[38:39] nt
	s_add_u32 s38, s38, s7
	s_addc_u32 s39, s39, 0
	global_load_dwordx4 v[178:181], v234, s[38:39] nt
	s_mov_b32 s4, 0
	s_mov_b32 s5, s2
	s_cmp_ge_u32 s5, 6784
	s_cselect_b32 s6, 6784, 0
	s_cselect_b32 s7, 1, 0
	s_sub_u32 s5, s5, s6
	s_add_u32 s4, s4, s7
	s_cmp_ge_u32 s5, 6784
	s_cselect_b32 s6, 6784, 0
	s_cselect_b32 s7, 1, 0
	s_sub_u32 s5, s5, s6
	s_add_u32 s4, s4, s7
	s_cmp_ge_u32 s5, 6784
	s_cselect_b32 s6, 6784, 0
	s_cselect_b32 s7, 1, 0
	s_sub_u32 s5, s5, s6
	s_add_u32 s4, s4, s7
	s_cmp_lt_u32 s5, 1408
	s_cbranch_scc1 .Lp0_d2_w0
	s_cmp_lt_u32 s5, 2112
	s_cbranch_scc1 .Lp0_d2_w1
	s_cmp_lt_u32 s5, 3904
	s_cbranch_scc1 .Lp0_d2_w2
	s_cmp_lt_u32 s5, 4160
	s_cbranch_scc1 .Lp0_d2_w3
	s_cmp_lt_u32 s5, 4416
	s_cbranch_scc1 .Lp0_d2_w4
	s_cmp_lt_u32 s5, 4672
	s_cbranch_scc1 .Lp0_d2_w5
	s_cmp_lt_u32 s5, 6080
	s_cbranch_scc1 .Lp0_d2_w6
	s_mov_b32 s6, 6080
	s_mov_b32 s7, 65536
	s_mov_b32 s8, 16
	s_mov_b32 s9, 2816
	s_mov_b32 s10, 4096
	s_mov_b32 s11, 0
	s_mov_b32 s12, 0xa8
	s_mov_b32 s13, 0x2f80000
	s_branch .Lp0_d2_j

.Lp0_d2_j:
	s_load_dwordx2 s[36:37], s[0:1], s12
	s_sub_u32 s5, s5, s6
	s_mul_i32 s14, s5, s7
	s_lshr_b32 s14, s14, 20
	s_mul_i32 s15, s14, s8
	s_sub_u32 s15, s5, s15
	s_mul_i32 s44, s4, s9
	s_lshl_b32 s45, s14, 6
	s_add_u32 s44, s44, s45
	s_mul_i32 s44, s44, s10
	s_lshr_b32 s45, s15, 1
	s_lshl_b32 s45, s45, 6
	s_and_b32 s6, s15, 1
	s_lshl_b32 s6, s6, 5
	s_add_u32 s45, s45, s6
	s_lshl_b32 s6, s15, 6
	s_cmp_lg_u32 s11, 0
	s_cselect_b32 s45, s45, s6
	s_cselect_b64 vcc, -1, 0
	s_lshl_b32 s45, s45, 2
	s_add_u32 s44, s44, s45
	v_cndmask_b32_e32 v234, v227, v228, vcc
	v_mul_lo_u32 v237, v226, s10
	v_add_u32_e32 v234, v234, v237
	s_mul_hi_u32 s45, s4, 0x3500000
	s_mul_i32 s6, s4, 0x3500000
	s_add_u32 s42, s48, s6
	s_addc_u32 s43, s49, s45
	s_add_u32 s42, s42, 0xf5ce000
	s_addc_u32 s43, s43, 0
	s_add_u32 s42, s42, s13
	s_addc_u32 s43, s43, 0
	s_mul_i32 s45, s15, s9
	s_lshl_b32 s45, s45, 7
	s_cmp_eq_u32 s9, 2816
	s_cselect_b32 s6, 1, 0
	s_or_b32 s6, s6, s11
	s_lshl_b32 s7, s14, 11
	s_lshl_b32 s8, s14, 7
	s_cmp_lg_u32 s6, 0
	s_cselect_b32 s7, s7, s8
	s_cselect_b64 vcc, -1, 0
	s_add_u32 s45, s45, s7
	s_add_u32 s42, s42, s45
	s_addc_u32 s43, s43, 0
	v_cndmask_b32_e32 v237, v231, v232, vcc
	s_cmp_eq_u32 s9, 2816
	s_cselect_b64 vcc, -1, 0
	s_nop 1
	v_cndmask_b32_e32 v236, v237, v233, vcc
	s_lshl_b32 s7, s10, 4
	s_waitcnt lgkmcnt(0)
	s_add_u32 s38, s36, s44
	s_addc_u32 s39, s37, 0
	s_add_u32 s2, s2, 512
	global_load_dwordx4 v[182:185], v234, s[38:39] nt
	s_add_u32 s38, s38, s7
	s_addc_u32 s39, s39, 0
	global_load_dwordx4 v[186:189], v234, s[38:39] nt
	s_add_u32 s38, s38, s7
	s_addc_u32 s39, s39, 0
	global_load_dwordx4 v[190:193], v234, s[38:39] nt
	s_add_u32 s38, s38, s7
	s_addc_u32 s39, s39, 0
	global_load_dwordx4 v[194:197], v234, s[38:39] nt
	s_waitcnt vmcnt(4)
	ds_write_b32 v229, v166 offset:0
	ds_write_b32 v229, v167 offset:4
	ds_write_b32 v229, v168 offset:8
	ds_write_b32 v229, v169 offset:12
	ds_write_b32 v229, v170 offset:4160
	ds_write_b32 v229, v171 offset:4164
	ds_write_b32 v229, v172 offset:4168
	ds_write_b32 v229, v173 offset:4172
	ds_write_b32 v229, v174 offset:8320
	ds_write_b32 v229, v175 offset:8324
	ds_write_b32 v229, v176 offset:8328
	ds_write_b32 v229, v177 offset:8332
	ds_write_b32 v229, v178 offset:12480
	ds_write_b32 v229, v179 offset:12484
	ds_write_b32 v229, v180 offset:12488
	ds_write_b32 v229, v181 offset:12492
	s_waitcnt lgkmcnt(0)
	s_barrier
	ds_read_b32 v198, v230 offset:0
	ds_read_b32 v199, v230 offset:260
	ds_read_b32 v200, v230 offset:520
	ds_read_b32 v201, v230 offset:780
	ds_read_b32 v202, v230 offset:1040
	ds_read_b32 v203, v230 offset:1300
	ds_read_b32 v204, v230 offset:1560
	ds_read_b32 v205, v230 offset:1820
	ds_read_b32 v206, v230 offset:2080
	ds_read_b32 v207, v230 offset:2340
	ds_read_b32 v208, v230 offset:2600
	ds_read_b32 v209, v230 offset:2860
	ds_read_b32 v210, v230 offset:3120
	ds_read_b32 v211, v230 offset:3380
	ds_read_b32 v212, v230 offset:3640
	ds_read_b32 v213, v230 offset:3900
	s_waitcnt lgkmcnt(14)
	v_cvt_pk_bf16_f32 v218, v198, v199
	s_waitcnt lgkmcnt(12)
	v_cvt_pk_bf16_f32 v219, v200, v201
	s_waitcnt lgkmcnt(10)
	v_cvt_pk_bf16_f32 v220, v202, v203
	s_waitcnt lgkmcnt(8)
	v_cvt_pk_bf16_f32 v221, v204, v205
	s_waitcnt lgkmcnt(6)
	v_cvt_pk_bf16_f32 v222, v206, v207
	s_waitcnt lgkmcnt(4)
	v_cvt_pk_bf16_f32 v223, v208, v209
	s_waitcnt lgkmcnt(2)
	v_cvt_pk_bf16_f32 v224, v210, v211
	s_waitcnt lgkmcnt(0)
	v_cvt_pk_bf16_f32 v225, v212, v213
	global_store_dwordx4 v235, v[218:221], s[40:41]
	global_store_dwordx4 v235, v[222:225], s[40:41] offset:16
	s_mov_b32 s4, 0
	s_mov_b32 s5, s2
	s_cmp_ge_u32 s5, 6784
	s_cselect_b32 s6, 6784, 0
	s_cselect_b32 s7, 1, 0
	s_sub_u32 s5, s5, s6
	s_add_u32 s4, s4, s7
	s_cmp_ge_u32 s5, 6784
	s_cselect_b32 s6, 6784, 0
	s_cselect_b32 s7, 1, 0
	s_sub_u32 s5, s5, s6
	s_add_u32 s4, s4, s7
	s_cmp_ge_u32 s5, 6784
	s_cselect_b32 s6, 6784, 0
	s_cselect_b32 s7, 1, 0
	s_sub_u32 s5, s5, s6
	s_add_u32 s4, s4, s7
	s_cmp_lt_u32 s5, 1408
	s_cbranch_scc1 .Lp0_d3_w0
	s_cmp_lt_u32 s5, 2112
	s_cbranch_scc1 .Lp0_d3_w1
	s_cmp_lt_u32 s5, 3904
	s_cbranch_scc1 .Lp0_d3_w2
	s_cmp_lt_u32 s5, 4160
	s_cbranch_scc1 .Lp0_d3_w3
	s_cmp_lt_u32 s5, 4416
	s_cbranch_scc1 .Lp0_d3_w4
	s_cmp_lt_u32 s5, 4672
	s_cbranch_scc1 .Lp0_d3_w5
	s_cmp_lt_u32 s5, 6080
	s_cbranch_scc1 .Lp0_d3_w6
	s_mov_b32 s6, 6080
	s_mov_b32 s7, 65536
	s_mov_b32 s8, 16
	s_mov_b32 s9, 2816
	s_mov_b32 s10, 4096
	s_mov_b32 s11, 0
	s_mov_b32 s12, 0xa8
	s_mov_b32 s13, 0x2f80000
	s_branch .Lp0_d3_j

.Lp0_d3_j:
	s_load_dwordx2 s[36:37], s[0:1], s12
	s_sub_u32 s5, s5, s6
	s_mul_i32 s14, s5, s7
	s_lshr_b32 s14, s14, 20
	s_mul_i32 s15, s14, s8
	s_sub_u32 s15, s5, s15
	s_mul_i32 s44, s4, s9
	s_lshl_b32 s45, s14, 6
	s_add_u32 s44, s44, s45
	s_mul_i32 s44, s44, s10
	s_lshr_b32 s45, s15, 1
	s_lshl_b32 s45, s45, 6
	s_and_b32 s6, s15, 1
	s_lshl_b32 s6, s6, 5
	s_add_u32 s45, s45, s6
	s_lshl_b32 s6, s15, 6
	s_cmp_lg_u32 s11, 0
	s_cselect_b32 s45, s45, s6
	s_cselect_b64 vcc, -1, 0
	s_lshl_b32 s45, s45, 2
	s_add_u32 s44, s44, s45
	v_cndmask_b32_e32 v234, v227, v228, vcc
	v_mul_lo_u32 v237, v226, s10
	v_add_u32_e32 v234, v234, v237
	s_mul_hi_u32 s45, s4, 0x3500000
	s_mul_i32 s6, s4, 0x3500000
	s_add_u32 s40, s48, s6
	s_addc_u32 s41, s49, s45
	s_add_u32 s40, s40, 0xf5ce000
	s_addc_u32 s41, s41, 0
	s_add_u32 s40, s40, s13
	s_addc_u32 s41, s41, 0
	s_mul_i32 s45, s15, s9
	s_lshl_b32 s45, s45, 7
	s_cmp_eq_u32 s9, 2816
	s_cselect_b32 s6, 1, 0
	s_or_b32 s6, s6, s11
	s_lshl_b32 s7, s14, 11
	s_lshl_b32 s8, s14, 7
	s_cmp_lg_u32 s6, 0
	s_cselect_b32 s7, s7, s8
	s_cselect_b64 vcc, -1, 0
	s_add_u32 s45, s45, s7
	s_add_u32 s40, s40, s45
	s_addc_u32 s41, s41, 0
	v_cndmask_b32_e32 v237, v231, v232, vcc
	s_cmp_eq_u32 s9, 2816
	s_cselect_b64 vcc, -1, 0
	s_nop 1
	v_cndmask_b32_e32 v235, v237, v233, vcc
	s_lshl_b32 s7, s10, 4
	s_waitcnt lgkmcnt(0)
	s_add_u32 s38, s36, s44
	s_addc_u32 s39, s37, 0
	s_add_u32 s2, s2, 512
	global_load_dwordx4 v[166:169], v234, s[38:39] nt
	s_add_u32 s38, s38, s7
	s_addc_u32 s39, s39, 0
	global_load_dwordx4 v[170:173], v234, s[38:39] nt
	s_add_u32 s38, s38, s7
	s_addc_u32 s39, s39, 0
	global_load_dwordx4 v[174:177], v234, s[38:39] nt
	s_add_u32 s38, s38, s7
	s_addc_u32 s39, s39, 0
	global_load_dwordx4 v[178:181], v234, s[38:39] nt
	s_waitcnt vmcnt(6)
	ds_write_b32 v229, v182 offset:33280
	ds_write_b32 v229, v183 offset:33284
	ds_write_b32 v229, v184 offset:33288
	ds_write_b32 v229, v185 offset:33292
	ds_write_b32 v229, v186 offset:37440
	ds_write_b32 v229, v187 offset:37444
	ds_write_b32 v229, v188 offset:37448
	ds_write_b32 v229, v189 offset:37452
	ds_write_b32 v229, v190 offset:41600
	ds_write_b32 v229, v191 offset:41604
	ds_write_b32 v229, v192 offset:41608
	ds_write_b32 v229, v193 offset:41612
	ds_write_b32 v229, v194 offset:45760
	ds_write_b32 v229, v195 offset:45764
	ds_write_b32 v229, v196 offset:45768
	ds_write_b32 v229, v197 offset:45772
	s_waitcnt lgkmcnt(0)
	s_barrier
	ds_read_b32 v198, v230 offset:33280
	ds_read_b32 v199, v230 offset:33540
	ds_read_b32 v200, v230 offset:33800
	ds_read_b32 v201, v230 offset:34060
	ds_read_b32 v202, v230 offset:34320
	ds_read_b32 v203, v230 offset:34580
	ds_read_b32 v204, v230 offset:34840
	ds_read_b32 v205, v230 offset:35100
	ds_read_b32 v206, v230 offset:35360
	ds_read_b32 v207, v230 offset:35620
	ds_read_b32 v208, v230 offset:35880
	ds_read_b32 v209, v230 offset:36140
	ds_read_b32 v210, v230 offset:36400
	ds_read_b32 v211, v230 offset:36660
	ds_read_b32 v212, v230 offset:36920
	ds_read_b32 v213, v230 offset:37180
	s_waitcnt lgkmcnt(14)
	v_cvt_pk_bf16_f32 v218, v198, v199
	s_waitcnt lgkmcnt(12)
	v_cvt_pk_bf16_f32 v219, v200, v201
	s_waitcnt lgkmcnt(10)
	v_cvt_pk_bf16_f32 v220, v202, v203
	s_waitcnt lgkmcnt(8)
	v_cvt_pk_bf16_f32 v221, v204, v205
	s_waitcnt lgkmcnt(6)
	v_cvt_pk_bf16_f32 v222, v206, v207
	s_waitcnt lgkmcnt(4)
	v_cvt_pk_bf16_f32 v223, v208, v209
	s_waitcnt lgkmcnt(2)
	v_cvt_pk_bf16_f32 v224, v210, v211
	s_waitcnt lgkmcnt(0)
	v_cvt_pk_bf16_f32 v225, v212, v213
	global_store_dwordx4 v236, v[218:221], s[42:43]
	global_store_dwordx4 v236, v[222:225], s[42:43] offset:16
	s_mov_b32 s3, 25
.Lp0_loop:
	s_mov_b32 s4, 0
	s_mov_b32 s5, s2
	s_cmp_ge_u32 s5, 6784
	s_cselect_b32 s6, 6784, 0
	s_cselect_b32 s7, 1, 0
	s_sub_u32 s5, s5, s6
	s_add_u32 s4, s4, s7
	s_cmp_ge_u32 s5, 6784
	s_cselect_b32 s6, 6784, 0
	s_cselect_b32 s7, 1, 0
	s_sub_u32 s5, s5, s6
	s_add_u32 s4, s4, s7
	s_cmp_ge_u32 s5, 6784
	s_cselect_b32 s6, 6784, 0
	s_cselect_b32 s7, 1, 0
	s_sub_u32 s5, s5, s6
	s_add_u32 s4, s4, s7
	s_cmp_lt_u32 s5, 1408
	s_cbranch_scc1 .Lp0_d4_w0
	s_cmp_lt_u32 s5, 2112
	s_cbranch_scc1 .Lp0_d4_w1
	s_cmp_lt_u32 s5, 3904
	s_cbranch_scc1 .Lp0_d4_w2
	s_cmp_lt_u32 s5, 4160
	s_cbranch_scc1 .Lp0_d4_w3
	s_cmp_lt_u32 s5, 4416
	s_cbranch_scc1 .Lp0_d4_w4
	s_cmp_lt_u32 s5, 4672
	s_cbranch_scc1 .Lp0_d4_w5
	s_cmp_lt_u32 s5, 6080
	s_cbranch_scc1 .Lp0_d4_w6
	s_mov_b32 s6, 6080
	s_mov_b32 s7, 65536
	s_mov_b32 s8, 16
	s_mov_b32 s9, 2816
	s_mov_b32 s10, 4096
	s_mov_b32 s11, 0
	s_mov_b32 s12, 0xa8
	s_mov_b32 s13, 0x2f80000
	s_branch .Lp0_d4_j

.Lp0_d4_j:
	s_load_dwordx2 s[36:37], s[0:1], s12
	s_sub_u32 s5, s5, s6
	s_mul_i32 s14, s5, s7
	s_lshr_b32 s14, s14, 20
	s_mul_i32 s15, s14, s8
	s_sub_u32 s15, s5, s15
	s_mul_i32 s44, s4, s9
	s_lshl_b32 s45, s14, 6
	s_add_u32 s44, s44, s45
	s_mul_i32 s44, s44, s10
	s_lshr_b32 s45, s15, 1
	s_lshl_b32 s45, s45, 6
	s_and_b32 s6, s15, 1
	s_lshl_b32 s6, s6, 5
	s_add_u32 s45, s45, s6
	s_lshl_b32 s6, s15, 6
	s_cmp_lg_u32 s11, 0
	s_cselect_b32 s45, s45, s6
	s_cselect_b64 vcc, -1, 0
	s_lshl_b32 s45, s45, 2
	s_add_u32 s44, s44, s45
	v_cndmask_b32_e32 v234, v227, v228, vcc
	v_mul_lo_u32 v237, v226, s10
	v_add_u32_e32 v234, v234, v237
	s_mul_hi_u32 s45, s4, 0x3500000
	s_mul_i32 s6, s4, 0x3500000
	s_add_u32 s42, s48, s6
	s_addc_u32 s43, s49, s45
	s_add_u32 s42, s42, 0xf5ce000
	s_addc_u32 s43, s43, 0
	s_add_u32 s42, s42, s13
	s_addc_u32 s43, s43, 0
	s_mul_i32 s45, s15, s9
	s_lshl_b32 s45, s45, 7
	s_cmp_eq_u32 s9, 2816
	s_cselect_b32 s6, 1, 0
	s_or_b32 s6, s6, s11
	s_lshl_b32 s7, s14, 11
	s_lshl_b32 s8, s14, 7
	s_cmp_lg_u32 s6, 0
	s_cselect_b32 s7, s7, s8
	s_cselect_b64 vcc, -1, 0
	s_add_u32 s45, s45, s7
	s_add_u32 s42, s42, s45
	s_addc_u32 s43, s43, 0
	v_cndmask_b32_e32 v237, v231, v232, vcc
	s_cmp_eq_u32 s9, 2816
	s_cselect_b64 vcc, -1, 0
	s_nop 1
	v_cndmask_b32_e32 v236, v237, v233, vcc
	s_lshl_b32 s7, s10, 4
	s_waitcnt lgkmcnt(0)
	s_add_u32 s38, s36, s44
	s_addc_u32 s39, s37, 0
	s_add_u32 s2, s2, 512
	global_load_dwordx4 v[182:185], v234, s[38:39] nt
	s_add_u32 s38, s38, s7
	s_addc_u32 s39, s39, 0
	global_load_dwordx4 v[186:189], v234, s[38:39] nt
	s_add_u32 s38, s38, s7
	s_addc_u32 s39, s39, 0
	global_load_dwordx4 v[190:193], v234, s[38:39] nt
	s_add_u32 s38, s38, s7
	s_addc_u32 s39, s39, 0
	global_load_dwordx4 v[194:197], v234, s[38:39] nt
	s_waitcnt vmcnt(6)
	ds_write_b32 v229, v166 offset:0
	ds_write_b32 v229, v167 offset:4
	ds_write_b32 v229, v168 offset:8
	ds_write_b32 v229, v169 offset:12
	ds_write_b32 v229, v170 offset:4160
	ds_write_b32 v229, v171 offset:4164
	ds_write_b32 v229, v172 offset:4168
	ds_write_b32 v229, v173 offset:4172
	ds_write_b32 v229, v174 offset:8320
	ds_write_b32 v229, v175 offset:8324
	ds_write_b32 v229, v176 offset:8328
	ds_write_b32 v229, v177 offset:8332
	ds_write_b32 v229, v178 offset:12480
	ds_write_b32 v229, v179 offset:12484
	ds_write_b32 v229, v180 offset:12488
	ds_write_b32 v229, v181 offset:12492
	s_waitcnt lgkmcnt(0)
	s_barrier
	ds_read_b32 v198, v230 offset:0
	ds_read_b32 v199, v230 offset:260
	ds_read_b32 v200, v230 offset:520
	ds_read_b32 v201, v230 offset:780
	ds_read_b32 v202, v230 offset:1040
	ds_read_b32 v203, v230 offset:1300
	ds_read_b32 v204, v230 offset:1560
	ds_read_b32 v205, v230 offset:1820
	ds_read_b32 v206, v230 offset:2080
	ds_read_b32 v207, v230 offset:2340
	ds_read_b32 v208, v230 offset:2600
	ds_read_b32 v209, v230 offset:2860
	ds_read_b32 v210, v230 offset:3120
	ds_read_b32 v211, v230 offset:3380
	ds_read_b32 v212, v230 offset:3640
	ds_read_b32 v213, v230 offset:3900
	s_waitcnt lgkmcnt(14)
	v_cvt_pk_bf16_f32 v218, v198, v199
	s_waitcnt lgkmcnt(12)
	v_cvt_pk_bf16_f32 v219, v200, v201
	s_waitcnt lgkmcnt(10)
	v_cvt_pk_bf16_f32 v220, v202, v203
	s_waitcnt lgkmcnt(8)
	v_cvt_pk_bf16_f32 v221, v204, v205
	s_waitcnt lgkmcnt(6)
	v_cvt_pk_bf16_f32 v222, v206, v207
	s_waitcnt lgkmcnt(4)
	v_cvt_pk_bf16_f32 v223, v208, v209
	s_waitcnt lgkmcnt(2)
	v_cvt_pk_bf16_f32 v224, v210, v211
	s_waitcnt lgkmcnt(0)
	v_cvt_pk_bf16_f32 v225, v212, v213
	global_store_dwordx4 v235, v[218:221], s[40:41]
	global_store_dwordx4 v235, v[222:225], s[40:41] offset:16
	s_mov_b32 s4, 0
	s_mov_b32 s5, s2
	s_cmp_ge_u32 s5, 6784
	s_cselect_b32 s6, 6784, 0
	s_cselect_b32 s7, 1, 0
	s_sub_u32 s5, s5, s6
	s_add_u32 s4, s4, s7
	s_cmp_ge_u32 s5, 6784
	s_cselect_b32 s6, 6784, 0
	s_cselect_b32 s7, 1, 0
	s_sub_u32 s5, s5, s6
	s_add_u32 s4, s4, s7
	s_cmp_ge_u32 s5, 6784
	s_cselect_b32 s6, 6784, 0
	s_cselect_b32 s7, 1, 0
	s_sub_u32 s5, s5, s6
	s_add_u32 s4, s4, s7
	s_cmp_lt_u32 s5, 1408
	s_cbranch_scc1 .Lp0_d5_w0
	s_cmp_lt_u32 s5, 2112
	s_cbranch_scc1 .Lp0_d5_w1
	s_cmp_lt_u32 s5, 3904
	s_cbranch_scc1 .Lp0_d5_w2
	s_cmp_lt_u32 s5, 4160
	s_cbranch_scc1 .Lp0_d5_w3
	s_cmp_lt_u32 s5, 4416
	s_cbranch_scc1 .Lp0_d5_w4
	s_cmp_lt_u32 s5, 4672
	s_cbranch_scc1 .Lp0_d5_w5
	s_cmp_lt_u32 s5, 6080
	s_cbranch_scc1 .Lp0_d5_w6
	s_mov_b32 s6, 6080
	s_mov_b32 s7, 65536
	s_mov_b32 s8, 16
	s_mov_b32 s9, 2816
	s_mov_b32 s10, 4096
	s_mov_b32 s11, 0
	s_mov_b32 s12, 0xa8
	s_mov_b32 s13, 0x2f80000
	s_branch .Lp0_d5_j

.Lp0_d5_j:
	s_load_dwordx2 s[36:37], s[0:1], s12
	s_sub_u32 s5, s5, s6
	s_mul_i32 s14, s5, s7
	s_lshr_b32 s14, s14, 20
	s_mul_i32 s15, s14, s8
	s_sub_u32 s15, s5, s15
	s_mul_i32 s44, s4, s9
	s_lshl_b32 s45, s14, 6
	s_add_u32 s44, s44, s45
	s_mul_i32 s44, s44, s10
	s_lshr_b32 s45, s15, 1
	s_lshl_b32 s45, s45, 6
	s_and_b32 s6, s15, 1
	s_lshl_b32 s6, s6, 5
	s_add_u32 s45, s45, s6
	s_lshl_b32 s6, s15, 6
	s_cmp_lg_u32 s11, 0
	s_cselect_b32 s45, s45, s6
	s_cselect_b64 vcc, -1, 0
	s_lshl_b32 s45, s45, 2
	s_add_u32 s44, s44, s45
	v_cndmask_b32_e32 v234, v227, v228, vcc
	v_mul_lo_u32 v237, v226, s10
	v_add_u32_e32 v234, v234, v237
	s_mul_hi_u32 s45, s4, 0x3500000
	s_mul_i32 s6, s4, 0x3500000
	s_add_u32 s40, s48, s6
	s_addc_u32 s41, s49, s45
	s_add_u32 s40, s40, 0xf5ce000
	s_addc_u32 s41, s41, 0
	s_add_u32 s40, s40, s13
	s_addc_u32 s41, s41, 0
	s_mul_i32 s45, s15, s9
	s_lshl_b32 s45, s45, 7
	s_cmp_eq_u32 s9, 2816
	s_cselect_b32 s6, 1, 0
	s_or_b32 s6, s6, s11
	s_lshl_b32 s7, s14, 11
	s_lshl_b32 s8, s14, 7
	s_cmp_lg_u32 s6, 0
	s_cselect_b32 s7, s7, s8
	s_cselect_b64 vcc, -1, 0
	s_add_u32 s45, s45, s7
	s_add_u32 s40, s40, s45
	s_addc_u32 s41, s41, 0
	v_cndmask_b32_e32 v237, v231, v232, vcc
	s_cmp_eq_u32 s9, 2816
	s_cselect_b64 vcc, -1, 0
	s_nop 1
	v_cndmask_b32_e32 v235, v237, v233, vcc
	s_lshl_b32 s7, s10, 4
	s_waitcnt lgkmcnt(0)
	s_add_u32 s38, s36, s44
	s_addc_u32 s39, s37, 0
	s_add_u32 s2, s2, 512
	global_load_dwordx4 v[166:169], v234, s[38:39] nt
	s_add_u32 s38, s38, s7
	s_addc_u32 s39, s39, 0
	global_load_dwordx4 v[170:173], v234, s[38:39] nt
	s_add_u32 s38, s38, s7
	s_addc_u32 s39, s39, 0
	global_load_dwordx4 v[174:177], v234, s[38:39] nt
	s_add_u32 s38, s38, s7
	s_addc_u32 s39, s39, 0
	global_load_dwordx4 v[178:181], v234, s[38:39] nt
	s_waitcnt vmcnt(6)
	ds_write_b32 v229, v182 offset:33280
	ds_write_b32 v229, v183 offset:33284
	ds_write_b32 v229, v184 offset:33288
	ds_write_b32 v229, v185 offset:33292
	ds_write_b32 v229, v186 offset:37440
	ds_write_b32 v229, v187 offset:37444
	ds_write_b32 v229, v188 offset:37448
	ds_write_b32 v229, v189 offset:37452
	ds_write_b32 v229, v190 offset:41600
	ds_write_b32 v229, v191 offset:41604
	ds_write_b32 v229, v192 offset:41608
	ds_write_b32 v229, v193 offset:41612
	ds_write_b32 v229, v194 offset:45760
	ds_write_b32 v229, v195 offset:45764
	ds_write_b32 v229, v196 offset:45768
	ds_write_b32 v229, v197 offset:45772
	s_waitcnt lgkmcnt(0)
	s_barrier
	ds_read_b32 v198, v230 offset:33280
	ds_read_b32 v199, v230 offset:33540
	ds_read_b32 v200, v230 offset:33800
	ds_read_b32 v201, v230 offset:34060
	ds_read_b32 v202, v230 offset:34320
	ds_read_b32 v203, v230 offset:34580
	ds_read_b32 v204, v230 offset:34840
	ds_read_b32 v205, v230 offset:35100
	ds_read_b32 v206, v230 offset:35360
	ds_read_b32 v207, v230 offset:35620
	ds_read_b32 v208, v230 offset:35880
	ds_read_b32 v209, v230 offset:36140
	ds_read_b32 v210, v230 offset:36400
	ds_read_b32 v211, v230 offset:36660
	ds_read_b32 v212, v230 offset:36920
	ds_read_b32 v213, v230 offset:37180
	s_waitcnt lgkmcnt(14)
	v_cvt_pk_bf16_f32 v218, v198, v199
	s_waitcnt lgkmcnt(12)
	v_cvt_pk_bf16_f32 v219, v200, v201
	s_waitcnt lgkmcnt(10)
	v_cvt_pk_bf16_f32 v220, v202, v203
	s_waitcnt lgkmcnt(8)
	v_cvt_pk_bf16_f32 v221, v204, v205
	s_waitcnt lgkmcnt(6)
	v_cvt_pk_bf16_f32 v222, v206, v207
	s_waitcnt lgkmcnt(4)
	v_cvt_pk_bf16_f32 v223, v208, v209
	s_waitcnt lgkmcnt(2)
	v_cvt_pk_bf16_f32 v224, v210, v211
	s_waitcnt lgkmcnt(0)
	v_cvt_pk_bf16_f32 v225, v212, v213
	global_store_dwordx4 v236, v[218:221], s[42:43]
	global_store_dwordx4 v236, v[222:225], s[42:43] offset:16
	s_sub_u32 s3, s3, 1
	s_cmp_lg_u32 s3, 0
	s_cbranch_scc1 .Lp0_loop
	s_waitcnt vmcnt(2)
	ds_write_b32 v229, v166 offset:0
	ds_write_b32 v229, v167 offset:4
	ds_write_b32 v229, v168 offset:8
	ds_write_b32 v229, v169 offset:12
	ds_write_b32 v229, v170 offset:4160
	ds_write_b32 v229, v171 offset:4164
	ds_write_b32 v229, v172 offset:4168
	ds_write_b32 v229, v173 offset:4172
	ds_write_b32 v229, v174 offset:8320
	ds_write_b32 v229, v175 offset:8324
	ds_write_b32 v229, v176 offset:8328
	ds_write_b32 v229, v177 offset:8332
	ds_write_b32 v229, v178 offset:12480
	ds_write_b32 v229, v179 offset:12484
	ds_write_b32 v229, v180 offset:12488
	ds_write_b32 v229, v181 offset:12492
	s_waitcnt lgkmcnt(0)
	s_barrier
	ds_read_b32 v198, v230 offset:0
	ds_read_b32 v199, v230 offset:260
	ds_read_b32 v200, v230 offset:520
	ds_read_b32 v201, v230 offset:780
	ds_read_b32 v202, v230 offset:1040
	ds_read_b32 v203, v230 offset:1300
	ds_read_b32 v204, v230 offset:1560
	ds_read_b32 v205, v230 offset:1820
	ds_read_b32 v206, v230 offset:2080
	ds_read_b32 v207, v230 offset:2340
	ds_read_b32 v208, v230 offset:2600
	ds_read_b32 v209, v230 offset:2860
	ds_read_b32 v210, v230 offset:3120
	ds_read_b32 v211, v230 offset:3380
	ds_read_b32 v212, v230 offset:3640
	ds_read_b32 v213, v230 offset:3900
	s_waitcnt lgkmcnt(14)
	v_cvt_pk_bf16_f32 v218, v198, v199
	s_waitcnt lgkmcnt(12)
	v_cvt_pk_bf16_f32 v219, v200, v201
	s_waitcnt lgkmcnt(10)
	v_cvt_pk_bf16_f32 v220, v202, v203
	s_waitcnt lgkmcnt(8)
	v_cvt_pk_bf16_f32 v221, v204, v205
	s_waitcnt lgkmcnt(6)
	v_cvt_pk_bf16_f32 v222, v206, v207
	s_waitcnt lgkmcnt(4)
	v_cvt_pk_bf16_f32 v223, v208, v209
	s_waitcnt lgkmcnt(2)
	v_cvt_pk_bf16_f32 v224, v210, v211
	s_waitcnt lgkmcnt(0)
	v_cvt_pk_bf16_f32 v225, v212, v213
	global_store_dwordx4 v235, v[218:221], s[40:41]
	global_store_dwordx4 v235, v[222:225], s[40:41] offset:16
	s_waitcnt lgkmcnt(0)
	s_barrier
	v_readlane_b32 s0, v249, 0
	v_readlane_b32 s1, v249, 1
	v_readlane_b32 s2, v249, 2
	v_readlane_b32 s3, v249, 3
	v_readlane_b32 s4, v249, 4
	v_readlane_b32 s5, v249, 5
	v_readlane_b32 s6, v249, 6
	v_readlane_b32 s7, v249, 7
	v_readlane_b32 s8, v249, 8
	v_readlane_b32 s9, v249, 9
	v_readlane_b32 s10, v249, 10
	v_readlane_b32 s11, v249, 11
	v_readlane_b32 s12, v249, 12
	v_readlane_b32 s13, v249, 13
	v_readlane_b32 s14, v249, 14
	v_readlane_b32 s15, v249, 15
	v_readlane_b32 s36, v249, 16
	v_readlane_b32 s37, v249, 17
	v_readlane_b32 s38, v249, 18
	v_readlane_b32 s39, v249, 19
	v_readlane_b32 s40, v249, 20
	v_readlane_b32 s41, v249, 21
	v_readlane_b32 s42, v249, 22
	v_readlane_b32 s43, v249, 23
	v_readlane_b32 s44, v249, 24
	v_readlane_b32 s45, v249, 25
	s_nop 0
	s_add_u32 s14, s14, 13568
	s_branch .LBB0_468
